# write-through (sc1) epilogue stores also in the GLU GEMM (P4): its output is read once, keeping it out of L2 leaves the cache to the streamed operands
# baseline (speedup 1.0000x reference)
; __device__ __forceinline__ unsigned cvt_pk(float lo, float hi) { unsigned r; asm volatile("v_cvt_pk_bf16_f32 %0, %1, %2" : "=v"(r) : "v"(lo), "v"(hi)); return r; }
; __device__ __forceinline__ float fast_sigmoid(float v) { return __builtin_amdgcn_rcpf(1.0f + __builtin_amdgcn_exp2f(-1.4426950408889634f * v)); }
;     __device__ __forceinline__ void operator()(const pg8::f32x4 (&acc)[2][2][4][2], const pg8::Unit& u, int wr, int wc, int fr, int fq) const {
;         const int row0 = u.pm * 256 + wr * 64 + fr, col0 = u.pn * 128 + wc * 32 + 8 * fq;
; #pragma unroll
;         for (int ai = 0; ai < 2; ++ai)
; #pragma unroll
;             for (int m = 0; m < 4; ++m) { const int row = row0 + ai * 128 + m * 16; float o[8]; float ss = 0.f;
; #pragma unroll
;                 for (int n = 0; n < 2; ++n)
; #pragma unroll
;                     for (int e = 0; e < 4; ++e) { const float v = acc[ai][0][m][n][e] * fast_sigmoid(acc[ai][1][m][n][e]); o[n * 4 + e] = v; ss += v * v; }
;                 u32x4 w; w.x = cvt_pk(o[0], o[1]); w.y = cvt_pk(o[2], o[3]); w.z = cvt_pk(o[4], o[5]); w.w = cvt_pk(o[6], o[7]);
;                 *(u32x4*)(O + (size_t)row * ldc + col0) = w;
;                 ss += __shfl_xor(ss, 16); ss += __shfl_xor(ss, 32);
;                 if (fq == 0) atomicAdd(rowsb + row, ss); }
;     }
.LBB0_415:
	v_mul_f32_e32 v122, 0xbfb8aa3b, v122
	v_mul_f32_e32 v112, 0xbfb8aa3b, v112
	v_exp_f32_e32 v122, v122
	v_exp_f32_e32 v112, v112
	v_mul_f32_e32 v120, 0xbfb8aa3b, v120
	v_exp_f32_e32 v120, v120
	v_mul_f32_e32 v121, 0xbfb8aa3b, v121
	v_add_f32_e32 v122, 1.0, v122
	v_add_f32_e32 v112, 1.0, v112
	v_mul_f32_e32 v113, 0xbfb8aa3b, v113
	v_exp_f32_e32 v121, v121
	v_rcp_f32_e32 v122, v122
	v_rcp_f32_e32 v112, v112
	v_exp_f32_e32 v113, v113
	v_mul_f32_e32 v123, 0xbfb8aa3b, v123
	v_add_f32_e32 v120, 1.0, v120
	v_exp_f32_e32 v123, v123
	v_rcp_f32_e32 v137, v120
	v_add_f32_e32 v120, 1.0, v121
	v_mul_f32_e32 v122, v126, v122
	v_mul_f32_e32 v126, v116, v112
	v_add_f32_e32 v112, 1.0, v113
	v_mul_f32_e32 v113, 0xbfb8aa3b, v114
	v_rcp_f32_e32 v145, v120
	v_rcp_f32_e32 v112, v112
	v_exp_f32_e32 v113, v113
	v_mul_f32_e32 v114, 0xbfb8aa3b, v115
	v_add_f32_e32 v123, 1.0, v123
	v_exp_f32_e32 v114, v114
	v_rcp_f32_e32 v123, v123
	v_mul_f32_e32 v125, v125, v145
	v_mul_f32_e32 v115, v117, v112
	v_add_f32_e32 v112, 1.0, v113
	v_mul_f32_e32 v124, v124, v137
	v_mul_f32_e32 v145, v125, v125
	v_rcp_f32_e32 v112, v112
	v_fmac_f32_e32 v145, v124, v124
	v_add_f32_e32 v113, 1.0, v114
	v_fmac_f32_e32 v145, v122, v122
	v_mul_f32_e32 v123, v127, v123
	v_rcp_f32_e32 v113, v113
	v_fmac_f32_e32 v145, v123, v123
	v_and_b32_e32 v117, 64, v144
	v_fmac_f32_e32 v145, v126, v126
	v_mul_f32_e32 v114, v118, v112
	v_cvt_pk_bf16_f32 v116, v124, v125
	v_xor_b32_e32 v112, 16, v144
	v_add_u32_e32 v124, 64, v117
	v_fmac_f32_e32 v145, v115, v115
	v_cmp_lt_i32_e32 vcc, v112, v124
	v_fmac_f32_e32 v145, v114, v114
	v_mul_f32_e32 v113, v119, v113
	v_cndmask_b32_e32 v112, v144, v112, vcc
	v_fmac_f32_e32 v145, v113, v113
	v_lshlrev_b32_e32 v112, 2, v112
	ds_bpermute_b32 v125, v112, v145
	v_cvt_pk_bf16_f32 v117, v122, v123
	v_cvt_pk_bf16_f32 v118, v126, v115
	v_cvt_pk_bf16_f32 v119, v114, v113
	v_xor_b32_e32 v113, 32, v144
	v_cmp_lt_i32_e32 vcc, v113, v124
	s_waitcnt lgkmcnt(0)
	v_add_f32_e32 v114, v145, v125
	v_lshl_add_u32 v136, s26, 8, v138
	v_cndmask_b32_e32 v113, v144, v113, vcc
	v_lshlrev_b32_e32 v113, 2, v113
	ds_bpermute_b32 v115, v113, v114
	v_ashrrev_i32_e32 v137, 31, v136
	v_lshl_or_b32 v120, s24, 7, v140
	v_lshlrev_b64 v[122:123], 11, v[136:137]
	v_ashrrev_i32_e32 v121, 31, v120
	v_lshl_add_u64 v[122:123], s[52:53], 0, v[122:123]
	v_lshl_add_u64 v[122:123], v[120:121], 1, v[122:123]
	global_store_dwordx4 v[122:123], v[116:119], off sc1
	s_and_saveexec_b64 s[24:25], s[4:5]
	s_cbranch_execz .LBB0_417
	v_lshl_add_u64 v[116:117], v[136:137], 2, s[10:11]
	s_waitcnt lgkmcnt(0)
	v_add_f32_e32 v114, v114, v115
	global_atomic_add_f32 v[116:117], v114, off
.LBB0_417:
	s_or_b64 exec, exec, s[24:25]
	v_mul_f32_e32 v105, 0xbfb8aa3b, v105
	v_mul_f32_e32 v96, 0xbfb8aa3b, v96
	v_exp_f32_e32 v105, v105
	v_exp_f32_e32 v96, v96
	v_mul_f32_e32 v104, 0xbfb8aa3b, v104
	v_mul_f32_e32 v97, 0xbfb8aa3b, v97
	v_add_f32_e32 v105, 1.0, v105
	v_add_f32_e32 v96, 1.0, v96
	v_exp_f32_e32 v104, v104
	v_rcp_f32_e32 v105, v105
	v_mul_f32_e32 v106, 0xbfb8aa3b, v106
	v_rcp_f32_e32 v96, v96
	v_exp_f32_e32 v97, v97
	v_exp_f32_e32 v106, v106
	v_mul_f32_e32 v107, 0xbfb8aa3b, v107
	v_exp_f32_e32 v107, v107
	v_add_f32_e32 v104, 1.0, v104
	v_mul_f32_e32 v105, v109, v105
	v_mul_f32_e32 v109, v100, v96
	v_add_f32_e32 v96, 1.0, v97
	v_mul_f32_e32 v97, 0xbfb8aa3b, v98
	v_rcp_f32_e32 v104, v104
	v_add_f32_e32 v106, 1.0, v106
	v_rcp_f32_e32 v96, v96
	v_exp_f32_e32 v97, v97
	v_mul_f32_e32 v98, 0xbfb8aa3b, v99
	v_rcp_f32_e32 v106, v106
	v_add_f32_e32 v107, 1.0, v107
	v_exp_f32_e32 v98, v98
	v_rcp_f32_e32 v107, v107
	v_mul_f32_e32 v104, v108, v104
	v_mul_f32_e32 v108, v105, v105
	v_mul_f32_e32 v99, v101, v96
	v_add_f32_e32 v96, 1.0, v97
	v_fmac_f32_e32 v108, v104, v104
	v_mul_f32_e32 v106, v110, v106
	v_rcp_f32_e32 v96, v96
	v_add_f32_e32 v97, 1.0, v98
	v_fmac_f32_e32 v108, v106, v106
	v_mul_f32_e32 v107, v111, v107
	v_rcp_f32_e32 v97, v97
	v_fmac_f32_e32 v108, v107, v107
	v_fmac_f32_e32 v108, v109, v109
	v_fmac_f32_e32 v108, v99, v99
	v_mul_f32_e32 v98, v102, v96
	v_fmac_f32_e32 v108, v98, v98
	v_mul_f32_e32 v97, v103, v97
	v_fmac_f32_e32 v108, v97, v97
	v_cvt_pk_bf16_f32 v100, v104, v105
	ds_bpermute_b32 v104, v112, v108
	v_cvt_pk_bf16_f32 v101, v106, v107
	v_cvt_pk_bf16_f32 v102, v109, v99
	v_cvt_pk_bf16_f32 v103, v98, v97
	v_or_b32_e32 v96, 16, v136
	s_waitcnt lgkmcnt(0)
	v_add_f32_e32 v98, v108, v104
	ds_bpermute_b32 v99, v113, v98
	v_ashrrev_i32_e32 v97, 31, v96
	v_lshlrev_b64 v[104:105], 11, v[96:97]
	v_lshl_add_u64 v[104:105], s[52:53], 0, v[104:105]
	v_lshl_add_u64 v[104:105], v[120:121], 1, v[104:105]
	global_store_dwordx4 v[104:105], v[100:103], off sc1
	s_and_saveexec_b64 s[24:25], s[4:5]
	s_cbranch_execz .LBB0_419
	v_lshl_add_u64 v[96:97], v[96:97], 2, s[10:11]
	s_waitcnt lgkmcnt(0)
	v_add_f32_e32 v98, v98, v99
	global_atomic_add_f32 v[96:97], v98, off
; __device__ __forceinline__ unsigned cvt_pk(float lo, float hi) { unsigned r; asm volatile("v_cvt_pk_bf16_f32 %0, %1, %2" : "=v"(r) : "v"(lo), "v"(hi)); return r; }
; __device__ __forceinline__ float fast_sigmoid(float v) { return __builtin_amdgcn_rcpf(1.0f + __builtin_amdgcn_exp2f(-1.4426950408889634f * v)); }
;     __device__ __forceinline__ void operator()(const pg8::f32x4 (&acc)[2][2][4][2], const pg8::Unit& u, int wr, int wc, int fr, int fq) const {
;         const int row0 = u.pm * 256 + wr * 64 + fr, col0 = u.pn * 128 + wc * 32 + 8 * fq;
; #pragma unroll
;         for (int ai = 0; ai < 2; ++ai)
; #pragma unroll
;             for (int m = 0; m < 4; ++m) { const int row = row0 + ai * 128 + m * 16; float o[8]; float ss = 0.f;
; #pragma unroll
;                 for (int n = 0; n < 2; ++n)
; #pragma unroll
;                     for (int e = 0; e < 4; ++e) { const float v = acc[ai][0][m][n][e] * fast_sigmoid(acc[ai][1][m][n][e]); o[n * 4 + e] = v; ss += v * v; }
;                 u32x4 w; w.x = cvt_pk(o[0], o[1]); w.y = cvt_pk(o[2], o[3]); w.z = cvt_pk(o[4], o[5]); w.w = cvt_pk(o[6], o[7]);
;                 *(u32x4*)(O + (size_t)row * ldc + col0) = w;
;                 ss += __shfl_xor(ss, 16); ss += __shfl_xor(ss, 32);
;                 if (fq == 0) atomicAdd(rowsb + row, ss); }
;     }
.LBB0_419:
	s_or_b64 exec, exec, s[24:25]
	v_mul_f32_e32 v89, 0xbfb8aa3b, v89
	v_mul_f32_e32 v80, 0xbfb8aa3b, v80
	v_exp_f32_e32 v89, v89
	v_exp_f32_e32 v80, v80
	v_mul_f32_e32 v88, 0xbfb8aa3b, v88
	v_mul_f32_e32 v81, 0xbfb8aa3b, v81
	v_add_f32_e32 v89, 1.0, v89
	v_add_f32_e32 v80, 1.0, v80
	v_exp_f32_e32 v88, v88
	v_rcp_f32_e32 v89, v89
	v_mul_f32_e32 v90, 0xbfb8aa3b, v90
	v_rcp_f32_e32 v80, v80
	v_exp_f32_e32 v81, v81
	v_exp_f32_e32 v90, v90
	v_mul_f32_e32 v91, 0xbfb8aa3b, v91
	v_exp_f32_e32 v91, v91
	v_add_f32_e32 v88, 1.0, v88
	v_mul_f32_e32 v89, v93, v89
	v_mul_f32_e32 v93, v84, v80
	v_add_f32_e32 v80, 1.0, v81
	v_mul_f32_e32 v81, 0xbfb8aa3b, v82
	v_rcp_f32_e32 v88, v88
	v_add_f32_e32 v90, 1.0, v90
	v_rcp_f32_e32 v80, v80
	v_exp_f32_e32 v81, v81
	v_mul_f32_e32 v82, 0xbfb8aa3b, v83
	v_rcp_f32_e32 v90, v90
	v_add_f32_e32 v91, 1.0, v91
	v_exp_f32_e32 v82, v82
	v_rcp_f32_e32 v91, v91
	v_mul_f32_e32 v88, v92, v88
	v_mul_f32_e32 v92, v89, v89
	v_mul_f32_e32 v83, v85, v80
	v_add_f32_e32 v80, 1.0, v81
	v_fmac_f32_e32 v92, v88, v88
	v_mul_f32_e32 v90, v94, v90
	v_rcp_f32_e32 v80, v80
	v_add_f32_e32 v81, 1.0, v82
	v_fmac_f32_e32 v92, v90, v90
	v_mul_f32_e32 v91, v95, v91
	v_rcp_f32_e32 v81, v81
	v_fmac_f32_e32 v92, v91, v91
	v_fmac_f32_e32 v92, v93, v93
	v_fmac_f32_e32 v92, v83, v83
	v_mul_f32_e32 v82, v86, v80
	v_fmac_f32_e32 v92, v82, v82
	v_mul_f32_e32 v81, v87, v81
	v_fmac_f32_e32 v92, v81, v81
	v_cvt_pk_bf16_f32 v84, v88, v89
	ds_bpermute_b32 v88, v112, v92
	v_cvt_pk_bf16_f32 v85, v90, v91
	v_cvt_pk_bf16_f32 v86, v93, v83
	v_cvt_pk_bf16_f32 v87, v82, v81
	v_or_b32_e32 v80, 32, v136
	s_waitcnt lgkmcnt(0)
	v_add_f32_e32 v82, v92, v88
	ds_bpermute_b32 v83, v113, v82
	v_ashrrev_i32_e32 v81, 31, v80
	v_lshlrev_b64 v[88:89], 11, v[80:81]
	v_lshl_add_u64 v[88:89], s[52:53], 0, v[88:89]
	v_lshl_add_u64 v[88:89], v[120:121], 1, v[88:89]
	global_store_dwordx4 v[88:89], v[84:87], off sc1
	s_and_saveexec_b64 s[24:25], s[4:5]
	s_cbranch_execz .LBB0_421
	v_lshl_add_u64 v[80:81], v[80:81], 2, s[10:11]
	s_waitcnt lgkmcnt(0)
	v_add_f32_e32 v82, v82, v83
	global_atomic_add_f32 v[80:81], v82, off
.LBB0_421:
	s_or_b64 exec, exec, s[24:25]
	v_mul_f32_e32 v73, 0xbfb8aa3b, v73
	v_mul_f32_e32 v64, 0xbfb8aa3b, v64
	v_exp_f32_e32 v73, v73
	v_exp_f32_e32 v64, v64
	v_mul_f32_e32 v72, 0xbfb8aa3b, v72
	v_mul_f32_e32 v65, 0xbfb8aa3b, v65
	v_add_f32_e32 v73, 1.0, v73
	v_add_f32_e32 v64, 1.0, v64
	v_exp_f32_e32 v72, v72
	v_rcp_f32_e32 v73, v73
	v_mul_f32_e32 v74, 0xbfb8aa3b, v74
	v_rcp_f32_e32 v64, v64
	v_exp_f32_e32 v65, v65
	v_exp_f32_e32 v74, v74
	v_mul_f32_e32 v75, 0xbfb8aa3b, v75
	v_exp_f32_e32 v75, v75
	v_add_f32_e32 v72, 1.0, v72
	v_mul_f32_e32 v73, v77, v73
	v_mul_f32_e32 v77, v68, v64
	v_add_f32_e32 v64, 1.0, v65
	v_mul_f32_e32 v65, 0xbfb8aa3b, v66
	v_rcp_f32_e32 v72, v72
	v_add_f32_e32 v74, 1.0, v74
	v_rcp_f32_e32 v64, v64
	v_exp_f32_e32 v65, v65
	v_mul_f32_e32 v66, 0xbfb8aa3b, v67
	v_rcp_f32_e32 v74, v74
	v_add_f32_e32 v75, 1.0, v75
	v_exp_f32_e32 v66, v66
	v_rcp_f32_e32 v75, v75
	v_mul_f32_e32 v72, v76, v72
	v_mul_f32_e32 v76, v73, v73
	v_mul_f32_e32 v67, v69, v64
	v_add_f32_e32 v64, 1.0, v65
	v_fmac_f32_e32 v76, v72, v72
	v_mul_f32_e32 v74, v78, v74
	v_rcp_f32_e32 v64, v64
	v_add_f32_e32 v65, 1.0, v66
	v_fmac_f32_e32 v76, v74, v74
	v_mul_f32_e32 v75, v79, v75
	v_rcp_f32_e32 v65, v65
	v_fmac_f32_e32 v76, v75, v75
	v_fmac_f32_e32 v76, v77, v77
	v_fmac_f32_e32 v76, v67, v67
	v_mul_f32_e32 v66, v70, v64
	v_fmac_f32_e32 v76, v66, v66
	v_mul_f32_e32 v65, v71, v65
	v_fmac_f32_e32 v76, v65, v65
	v_cvt_pk_bf16_f32 v68, v72, v73
	ds_bpermute_b32 v72, v112, v76
	v_cvt_pk_bf16_f32 v69, v74, v75
	v_cvt_pk_bf16_f32 v70, v77, v67
	v_cvt_pk_bf16_f32 v71, v66, v65
	v_or_b32_e32 v64, 48, v136
	s_waitcnt lgkmcnt(0)
	v_add_f32_e32 v66, v76, v72
	ds_bpermute_b32 v67, v113, v66
	v_ashrrev_i32_e32 v65, 31, v64
	v_lshlrev_b64 v[72:73], 11, v[64:65]
	v_lshl_add_u64 v[72:73], s[52:53], 0, v[72:73]
	v_lshl_add_u64 v[72:73], v[120:121], 1, v[72:73]
	global_store_dwordx4 v[72:73], v[68:71], off sc1
	s_and_saveexec_b64 s[24:25], s[4:5]
	s_cbranch_execz .LBB0_423
	v_lshl_add_u64 v[64:65], v[64:65], 2, s[10:11]
	s_waitcnt lgkmcnt(0)
	v_add_f32_e32 v66, v66, v67
	global_atomic_add_f32 v[64:65], v66, off
.LBB0_423:
	s_or_b64 exec, exec, s[24:25]
	v_mul_f32_e32 v57, 0xbfb8aa3b, v57
	v_mul_f32_e32 v56, 0xbfb8aa3b, v56
	v_exp_f32_e32 v57, v57
	v_exp_f32_e32 v56, v56
	v_mul_f32_e32 v58, 0xbfb8aa3b, v58
	v_exp_f32_e32 v58, v58
	v_mul_f32_e32 v59, 0xbfb8aa3b, v59
	v_exp_f32_e32 v59, v59
	v_mul_f32_e32 v48, 0xbfb8aa3b, v48
	v_add_f32_e32 v57, 1.0, v57
	v_exp_f32_e32 v48, v48
	v_mul_f32_e32 v49, 0xbfb8aa3b, v49
	v_add_f32_e32 v56, 1.0, v56
	v_rcp_f32_e32 v57, v57
	v_exp_f32_e32 v49, v49
	v_mul_f32_e32 v50, 0xbfb8aa3b, v50
	v_rcp_f32_e32 v64, v56
	v_add_f32_e32 v58, 1.0, v58
	v_exp_f32_e32 v50, v50
	v_mul_f32_e32 v51, 0xbfb8aa3b, v51
	v_rcp_f32_e32 v58, v58
	v_add_f32_e32 v59, 1.0, v59
	v_exp_f32_e32 v51, v51
	v_rcp_f32_e32 v59, v59
	v_add_f32_e32 v48, 1.0, v48
	v_mul_f32_e32 v57, v61, v57
	v_rcp_f32_e32 v48, v48
	v_add_f32_e32 v49, 1.0, v49
	v_mul_f32_e32 v60, v60, v64
	v_mul_f32_e32 v61, v57, v57
	v_rcp_f32_e32 v49, v49
	v_add_f32_e32 v50, 1.0, v50
	v_fmac_f32_e32 v61, v60, v60
	v_mul_f32_e32 v58, v62, v58
	v_rcp_f32_e32 v50, v50
	v_add_f32_e32 v51, 1.0, v51
	v_fmac_f32_e32 v61, v58, v58
	v_mul_f32_e32 v59, v63, v59
	v_rcp_f32_e32 v51, v51
	v_fmac_f32_e32 v61, v59, v59
	v_mul_f32_e32 v48, v52, v48
	v_fmac_f32_e32 v61, v48, v48
	v_mul_f32_e32 v49, v53, v49
	v_fmac_f32_e32 v61, v49, v49
	v_mul_f32_e32 v53, v54, v50
	v_fmac_f32_e32 v61, v53, v53
	v_mul_f32_e32 v54, v55, v51
	v_fmac_f32_e32 v61, v54, v54
	ds_bpermute_b32 v55, v112, v61
	v_cvt_pk_bf16_f32 v50, v60, v57
	v_cvt_pk_bf16_f32 v51, v58, v59
	v_cvt_pk_bf16_f32 v52, v48, v49
	v_add_u32_e32 v56, 0x80, v136
	s_waitcnt lgkmcnt(0)
	v_add_f32_e32 v48, v61, v55
	ds_bpermute_b32 v49, v113, v48
	v_ashrrev_i32_e32 v57, 31, v56
	v_cvt_pk_bf16_f32 v53, v53, v54
	v_lshlrev_b64 v[54:55], 11, v[56:57]
	v_lshl_add_u64 v[54:55], s[52:53], 0, v[54:55]
	v_lshl_add_u64 v[54:55], v[120:121], 1, v[54:55]
	global_store_dwordx4 v[54:55], v[50:53], off sc1
	s_and_saveexec_b64 s[24:25], s[4:5]
	s_cbranch_execz .LBB0_425
	v_lshl_add_u64 v[50:51], v[56:57], 2, s[10:11]
	s_waitcnt lgkmcnt(0)
	v_add_f32_e32 v48, v48, v49
	global_atomic_add_f32 v[50:51], v48, off
; __device__ __forceinline__ unsigned cvt_pk(float lo, float hi) { unsigned r; asm volatile("v_cvt_pk_bf16_f32 %0, %1, %2" : "=v"(r) : "v"(lo), "v"(hi)); return r; }
; __device__ __forceinline__ float fast_sigmoid(float v) { return __builtin_amdgcn_rcpf(1.0f + __builtin_amdgcn_exp2f(-1.4426950408889634f * v)); }
;     __device__ __forceinline__ void operator()(const pg8::f32x4 (&acc)[2][2][4][2], const pg8::Unit& u, int wr, int wc, int fr, int fq) const {
;         const int row0 = u.pm * 256 + wr * 64 + fr, col0 = u.pn * 128 + wc * 32 + 8 * fq;
; #pragma unroll
;         for (int ai = 0; ai < 2; ++ai)
; #pragma unroll
;             for (int m = 0; m < 4; ++m) { const int row = row0 + ai * 128 + m * 16; float o[8]; float ss = 0.f;
; #pragma unroll
;                 for (int n = 0; n < 2; ++n)
; #pragma unroll
;                     for (int e = 0; e < 4; ++e) { const float v = acc[ai][0][m][n][e] * fast_sigmoid(acc[ai][1][m][n][e]); o[n * 4 + e] = v; ss += v * v; }
;                 u32x4 w; w.x = cvt_pk(o[0], o[1]); w.y = cvt_pk(o[2], o[3]); w.z = cvt_pk(o[4], o[5]); w.w = cvt_pk(o[6], o[7]);
;                 *(u32x4*)(O + (size_t)row * ldc + col0) = w;
;                 ss += __shfl_xor(ss, 16); ss += __shfl_xor(ss, 32);
;                 if (fq == 0) atomicAdd(rowsb + row, ss); }
;     }
.LBB0_425:
	s_or_b64 exec, exec, s[24:25]
	v_mul_f32_e32 v41, 0xbfb8aa3b, v41
	v_mul_f32_e32 v32, 0xbfb8aa3b, v32
	v_exp_f32_e32 v41, v41
	v_exp_f32_e32 v32, v32
	v_mul_f32_e32 v40, 0xbfb8aa3b, v40
	v_mul_f32_e32 v33, 0xbfb8aa3b, v33
	v_add_f32_e32 v41, 1.0, v41
	v_add_f32_e32 v32, 1.0, v32
	v_exp_f32_e32 v40, v40
	v_rcp_f32_e32 v41, v41
	v_mul_f32_e32 v42, 0xbfb8aa3b, v42
	v_rcp_f32_e32 v32, v32
	v_exp_f32_e32 v33, v33
	v_exp_f32_e32 v42, v42
	v_mul_f32_e32 v43, 0xbfb8aa3b, v43
	v_exp_f32_e32 v43, v43
	v_add_f32_e32 v40, 1.0, v40
	v_mul_f32_e32 v41, v45, v41
	v_mul_f32_e32 v45, v36, v32
	v_add_f32_e32 v32, 1.0, v33
	v_mul_f32_e32 v33, 0xbfb8aa3b, v34
	v_rcp_f32_e32 v40, v40
	v_add_f32_e32 v42, 1.0, v42
	v_rcp_f32_e32 v32, v32
	v_exp_f32_e32 v33, v33
	v_mul_f32_e32 v34, 0xbfb8aa3b, v35
	v_rcp_f32_e32 v42, v42
	v_add_f32_e32 v43, 1.0, v43
	v_exp_f32_e32 v34, v34
	v_rcp_f32_e32 v43, v43
	v_mul_f32_e32 v40, v44, v40
	v_mul_f32_e32 v44, v41, v41
	v_mul_f32_e32 v35, v37, v32
	v_add_f32_e32 v32, 1.0, v33
	v_fmac_f32_e32 v44, v40, v40
	v_mul_f32_e32 v42, v46, v42
	v_rcp_f32_e32 v32, v32
	v_add_f32_e32 v33, 1.0, v34
	v_fmac_f32_e32 v44, v42, v42
	v_mul_f32_e32 v43, v47, v43
	v_rcp_f32_e32 v33, v33
	v_fmac_f32_e32 v44, v43, v43
	v_fmac_f32_e32 v44, v45, v45
	v_fmac_f32_e32 v44, v35, v35
	v_mul_f32_e32 v34, v38, v32
	v_fmac_f32_e32 v44, v34, v34
	v_mul_f32_e32 v33, v39, v33
	v_fmac_f32_e32 v44, v33, v33
	v_cvt_pk_bf16_f32 v36, v40, v41
	ds_bpermute_b32 v40, v112, v44
	v_cvt_pk_bf16_f32 v37, v42, v43
	v_cvt_pk_bf16_f32 v38, v45, v35
	v_cvt_pk_bf16_f32 v39, v34, v33
	v_add_u32_e32 v32, 0x90, v136
	s_waitcnt lgkmcnt(0)
	v_add_f32_e32 v34, v44, v40
	ds_bpermute_b32 v35, v113, v34
	v_ashrrev_i32_e32 v33, 31, v32
	v_lshlrev_b64 v[40:41], 11, v[32:33]
	v_lshl_add_u64 v[40:41], s[52:53], 0, v[40:41]
	v_lshl_add_u64 v[40:41], v[120:121], 1, v[40:41]
	global_store_dwordx4 v[40:41], v[36:39], off sc1
	s_and_saveexec_b64 s[24:25], s[4:5]
	s_cbranch_execz .LBB0_427
	v_lshl_add_u64 v[32:33], v[32:33], 2, s[10:11]
	s_waitcnt lgkmcnt(0)
	v_add_f32_e32 v34, v34, v35
	global_atomic_add_f32 v[32:33], v34, off
.LBB0_427:
	s_or_b64 exec, exec, s[24:25]
	v_mul_f32_e32 v25, 0xbfb8aa3b, v25
	v_mul_f32_e32 v16, 0xbfb8aa3b, v16
	v_exp_f32_e32 v25, v25
	v_exp_f32_e32 v16, v16
	v_mul_f32_e32 v24, 0xbfb8aa3b, v24
	v_mul_f32_e32 v17, 0xbfb8aa3b, v17
	v_add_f32_e32 v25, 1.0, v25
	v_add_f32_e32 v16, 1.0, v16
	v_exp_f32_e32 v24, v24
	v_rcp_f32_e32 v25, v25
	v_mul_f32_e32 v26, 0xbfb8aa3b, v26
	v_rcp_f32_e32 v16, v16
	v_exp_f32_e32 v17, v17
	v_exp_f32_e32 v26, v26
	v_mul_f32_e32 v27, 0xbfb8aa3b, v27
	v_exp_f32_e32 v27, v27
	v_add_f32_e32 v24, 1.0, v24
	v_mul_f32_e32 v25, v29, v25
	v_mul_f32_e32 v29, v20, v16
	v_add_f32_e32 v16, 1.0, v17
	v_mul_f32_e32 v17, 0xbfb8aa3b, v18
	v_rcp_f32_e32 v24, v24
	v_add_f32_e32 v26, 1.0, v26
	v_rcp_f32_e32 v16, v16
	v_exp_f32_e32 v17, v17
	v_mul_f32_e32 v18, 0xbfb8aa3b, v19
	v_rcp_f32_e32 v26, v26
	v_add_f32_e32 v27, 1.0, v27
	v_exp_f32_e32 v18, v18
	v_rcp_f32_e32 v27, v27
	v_mul_f32_e32 v24, v28, v24
	v_mul_f32_e32 v28, v25, v25
	v_mul_f32_e32 v19, v21, v16
	v_add_f32_e32 v16, 1.0, v17
	v_fmac_f32_e32 v28, v24, v24
	v_mul_f32_e32 v26, v30, v26
	v_rcp_f32_e32 v16, v16
	v_add_f32_e32 v17, 1.0, v18
	v_fmac_f32_e32 v28, v26, v26
	v_mul_f32_e32 v27, v31, v27
	v_rcp_f32_e32 v17, v17
	v_fmac_f32_e32 v28, v27, v27
	v_fmac_f32_e32 v28, v29, v29
	v_fmac_f32_e32 v28, v19, v19
	v_mul_f32_e32 v18, v22, v16
	v_fmac_f32_e32 v28, v18, v18
	v_mul_f32_e32 v17, v23, v17
	v_fmac_f32_e32 v28, v17, v17
	v_cvt_pk_bf16_f32 v20, v24, v25
	ds_bpermute_b32 v24, v112, v28
	v_cvt_pk_bf16_f32 v21, v26, v27
	v_cvt_pk_bf16_f32 v22, v29, v19
	v_cvt_pk_bf16_f32 v23, v18, v17
	v_add_u32_e32 v16, 0xa0, v136
	s_waitcnt lgkmcnt(0)
	v_add_f32_e32 v18, v28, v24
	ds_bpermute_b32 v19, v113, v18
	v_ashrrev_i32_e32 v17, 31, v16
	v_lshlrev_b64 v[24:25], 11, v[16:17]
	v_lshl_add_u64 v[24:25], s[52:53], 0, v[24:25]
	v_lshl_add_u64 v[24:25], v[120:121], 1, v[24:25]
	global_store_dwordx4 v[24:25], v[20:23], off sc1
	s_and_saveexec_b64 s[24:25], s[4:5]
	s_cbranch_execz .LBB0_429
	v_lshl_add_u64 v[16:17], v[16:17], 2, s[10:11]
	s_waitcnt lgkmcnt(0)
	v_add_f32_e32 v18, v18, v19
	global_atomic_add_f32 v[16:17], v18, off
.LBB0_429:
	s_or_b64 exec, exec, s[24:25]
	v_mul_f32_e32 v9, 0xbfb8aa3b, v9
	v_mul_f32_e32 v0, 0xbfb8aa3b, v0
	v_exp_f32_e32 v9, v9
	v_exp_f32_e32 v0, v0
	v_mul_f32_e32 v8, 0xbfb8aa3b, v8
	v_mul_f32_e32 v1, 0xbfb8aa3b, v1
	v_add_f32_e32 v9, 1.0, v9
	v_add_f32_e32 v0, 1.0, v0
	v_exp_f32_e32 v8, v8
	v_rcp_f32_e32 v9, v9
	v_mul_f32_e32 v10, 0xbfb8aa3b, v10
	v_rcp_f32_e32 v0, v0
	v_exp_f32_e32 v1, v1
	v_exp_f32_e32 v10, v10
	v_mul_f32_e32 v11, 0xbfb8aa3b, v11
	v_exp_f32_e32 v11, v11
	v_add_f32_e32 v8, 1.0, v8
	v_mul_f32_e32 v9, v13, v9
	v_mul_f32_e32 v13, v4, v0
	v_add_f32_e32 v0, 1.0, v1
	v_mul_f32_e32 v1, 0xbfb8aa3b, v2
	v_rcp_f32_e32 v8, v8
	v_add_f32_e32 v10, 1.0, v10
	v_rcp_f32_e32 v0, v0
	v_exp_f32_e32 v1, v1
	v_mul_f32_e32 v2, 0xbfb8aa3b, v3
	v_rcp_f32_e32 v10, v10
	v_add_f32_e32 v11, 1.0, v11
	v_exp_f32_e32 v2, v2
	v_rcp_f32_e32 v11, v11
	v_mul_f32_e32 v8, v12, v8
	v_mul_f32_e32 v12, v9, v9
	v_mul_f32_e32 v3, v5, v0
	v_add_f32_e32 v0, 1.0, v1
	v_fmac_f32_e32 v12, v8, v8
	v_mul_f32_e32 v10, v14, v10
	v_rcp_f32_e32 v0, v0
	v_add_f32_e32 v1, 1.0, v2
	v_fmac_f32_e32 v12, v10, v10
	v_mul_f32_e32 v11, v15, v11
	v_rcp_f32_e32 v1, v1
	v_fmac_f32_e32 v12, v11, v11
	v_fmac_f32_e32 v12, v13, v13
	v_fmac_f32_e32 v12, v3, v3
	v_mul_f32_e32 v2, v6, v0
	v_fmac_f32_e32 v12, v2, v2
	v_mul_f32_e32 v1, v7, v1
	v_fmac_f32_e32 v12, v1, v1
	v_cvt_pk_bf16_f32 v4, v8, v9
	ds_bpermute_b32 v8, v112, v12
	v_cvt_pk_bf16_f32 v5, v10, v11
	v_cvt_pk_bf16_f32 v6, v13, v3
	v_cvt_pk_bf16_f32 v7, v2, v1
	v_add_u32_e32 v0, 0xb0, v136
	s_waitcnt lgkmcnt(0)
	v_add_f32_e32 v2, v12, v8
	ds_bpermute_b32 v3, v113, v2
	v_ashrrev_i32_e32 v1, 31, v0
	v_lshlrev_b64 v[8:9], 11, v[0:1]
	v_lshl_add_u64 v[8:9], s[52:53], 0, v[8:9]
	v_lshl_add_u64 v[8:9], v[120:121], 1, v[8:9]
	global_store_dwordx4 v[8:9], v[4:7], off sc1
	s_and_saveexec_b64 s[24:25], s[4:5]
	s_cbranch_execz .LBB0_431
	v_lshl_add_u64 v[0:1], v[0:1], 2, s[10:11]
	s_waitcnt lgkmcnt(0)
	v_add_f32_e32 v2, v2, v3
	global_atomic_add_f32 v[0:1], v2, off
